# FFN-up K-loops: LDS-DMA loads addressed as SGPR base + 32-bit VGPR offset (no per-load 64-bit VALU address adds)
# baseline (speedup 1.0000x reference)
.LBB0_251:
	ds_read_b128 v[154:157], v151
	ds_read_b128 v[158:161], v151 offset:1024
	ds_read_b128 v[162:165], v151 offset:2048
	ds_read_b128 v[166:169], v151 offset:3072
	ds_read_b128 v[170:173], v152
	ds_read_b128 v[174:177], v152 offset:1024
	ds_read_b128 v[178:181], v152 offset:2048
	ds_read_b128 v[186:189], v152 offset:3072
	s_add_u32 s38, s36, 0xfff80080
	s_addc_u32 s39, s37, -1
	s_cmp_eq_u32 s74, 28
	s_cselect_b32 s45, s25, s39
	s_cselect_b32 s44, s34, s38
	s_cselect_b32 s39, s23, s71
	s_cselect_b32 s38, s35, s70
	s_mov_b64 s[98:99], s[44:45]
	s_add_i32 m0, s31, 0xc000
	ds_read_b128 v[190:193], v153
	ds_read_b128 v[194:197], v153 offset:1024
	ds_read_b128 v[202:205], v153 offset:2048
	ds_read_b128 v[206:209], v153 offset:3072
	ds_read_b128 v[210:213], v153 offset:4096
	ds_read_b128 v[214:217], v153 offset:5120
	ds_read_b128 v[226:229], v153 offset:6144
	ds_read_b128 v[230:233], v153 offset:7168
	global_load_lds_dwordx4 v142, s[36:37]
	s_add_i32 m0, s31, 0xe000
	s_nop 0
	global_load_lds_dwordx4 v140, s[36:37]
	s_waitcnt vmcnt(8)
	s_waitcnt lgkmcnt(0)
	s_barrier
	s_setprio 1
	s_waitcnt lgkmcnt(0)
	v_mfma_f32_16x16x32_bf16 v[126:129], v[154:157], v[190:193], v[126:129]
	v_mfma_f32_16x16x32_bf16 v[126:129], v[158:161], v[194:197], v[126:129]
	v_mfma_f32_16x16x32_bf16 v[122:125], v[162:165], v[190:193], v[122:125]
	v_mfma_f32_16x16x32_bf16 v[122:125], v[166:169], v[194:197], v[122:125]
	v_mfma_f32_16x16x32_bf16 v[118:121], v[170:173], v[190:193], v[118:121]
	v_mfma_f32_16x16x32_bf16 v[118:121], v[174:177], v[194:197], v[118:121]
	v_mfma_f32_16x16x32_bf16 v[114:117], v[178:181], v[190:193], v[114:117]
	v_mfma_f32_16x16x32_bf16 v[114:117], v[186:189], v[194:197], v[114:117]
	v_mfma_f32_16x16x32_bf16 v[110:113], v[154:157], v[202:205], v[110:113]
	v_mfma_f32_16x16x32_bf16 v[110:113], v[158:161], v[206:209], v[110:113]
	v_mfma_f32_16x16x32_bf16 v[106:109], v[162:165], v[202:205], v[106:109]
	v_mfma_f32_16x16x32_bf16 v[106:109], v[166:169], v[206:209], v[106:109]
	v_mfma_f32_16x16x32_bf16 v[102:105], v[170:173], v[202:205], v[102:105]
	v_mfma_f32_16x16x32_bf16 v[102:105], v[174:177], v[206:209], v[102:105]
	v_mfma_f32_16x16x32_bf16 v[98:101], v[178:181], v[202:205], v[98:101]
	v_mfma_f32_16x16x32_bf16 v[98:101], v[186:189], v[206:209], v[98:101]
	s_setprio 0
	s_setprio 1
	v_mfma_f32_16x16x32_bf16 v[94:97], v[154:157], v[210:213], v[94:97]
	v_mfma_f32_16x16x32_bf16 v[94:97], v[158:161], v[214:217], v[94:97]
	v_mfma_f32_16x16x32_bf16 v[90:93], v[162:165], v[210:213], v[90:93]
	v_mfma_f32_16x16x32_bf16 v[90:93], v[166:169], v[214:217], v[90:93]
	v_mfma_f32_16x16x32_bf16 v[86:89], v[170:173], v[210:213], v[86:89]
	v_mfma_f32_16x16x32_bf16 v[86:89], v[174:177], v[214:217], v[86:89]
	v_mfma_f32_16x16x32_bf16 v[82:85], v[178:181], v[210:213], v[82:85]
	v_mfma_f32_16x16x32_bf16 v[82:85], v[186:189], v[214:217], v[82:85]
	v_mfma_f32_16x16x32_bf16 v[78:81], v[154:157], v[226:229], v[78:81]
	v_mfma_f32_16x16x32_bf16 v[78:81], v[158:161], v[230:233], v[78:81]
	v_mfma_f32_16x16x32_bf16 v[74:77], v[162:165], v[226:229], v[74:77]
	v_mfma_f32_16x16x32_bf16 v[74:77], v[166:169], v[230:233], v[74:77]
	v_mfma_f32_16x16x32_bf16 v[70:73], v[170:173], v[226:229], v[70:73]
	v_mfma_f32_16x16x32_bf16 v[70:73], v[174:177], v[230:233], v[70:73]
	v_mfma_f32_16x16x32_bf16 v[66:69], v[178:181], v[226:229], v[66:69]
	v_mfma_f32_16x16x32_bf16 v[66:69], v[186:189], v[230:233], v[66:69]
	s_setprio 0
	s_barrier
	s_add_i32 s76, s66, s53
	s_mov_b32 m0, s76
	ds_read_b128 v[190:193], v153 offset:16384
	ds_read_b128 v[194:197], v153 offset:17408
	ds_read_b128 v[202:205], v153 offset:18432
	ds_read_b128 v[206:209], v153 offset:19456
	ds_read_b128 v[210:213], v153 offset:20480
	ds_read_b128 v[214:217], v153 offset:21504
	ds_read_b128 v[226:229], v153 offset:22528
	ds_read_b128 v[230:233], v153 offset:23552
	global_load_lds_dwordx4 v134, s[38:39]
	s_add_i32 m0, s76, 0x2000
	s_add_u32 s76, s38, 0x80000
	s_addc_u32 s77, s39, 0
	s_add_i32 s78, s67, s53
	global_load_lds_dwordx4 v130, s[38:39]
	s_mov_b32 m0, s78
	s_nop 0
	global_load_lds_dwordx4 v134, s[76:77]
	s_add_i32 m0, s78, 0x2000
	s_nop 0
	global_load_lds_dwordx4 v130, s[76:77]
	s_mov_b32 m0, s31
	s_nop 0
	global_load_lds_dwordx4 v136, s[44:45]
	s_mov_b32 m0, s56
	s_nop 0
	global_load_lds_dwordx4 v132, s[44:45]
	s_waitcnt vmcnt(8)
	s_waitcnt lgkmcnt(0)
	s_barrier
	s_setprio 1
	s_waitcnt lgkmcnt(0)
	v_mfma_f32_16x16x32_bf16 v[62:65], v[154:157], v[190:193], v[62:65]
	v_mfma_f32_16x16x32_bf16 v[62:65], v[158:161], v[194:197], v[62:65]
	v_mfma_f32_16x16x32_bf16 v[58:61], v[162:165], v[190:193], v[58:61]
	v_mfma_f32_16x16x32_bf16 v[58:61], v[166:169], v[194:197], v[58:61]
	v_mfma_f32_16x16x32_bf16 v[54:57], v[170:173], v[190:193], v[54:57]
	v_mfma_f32_16x16x32_bf16 v[54:57], v[174:177], v[194:197], v[54:57]
	v_mfma_f32_16x16x32_bf16 v[50:53], v[178:181], v[190:193], v[50:53]
	v_mfma_f32_16x16x32_bf16 v[50:53], v[186:189], v[194:197], v[50:53]
	v_mfma_f32_16x16x32_bf16 v[46:49], v[154:157], v[202:205], v[46:49]
	v_mfma_f32_16x16x32_bf16 v[46:49], v[158:161], v[206:209], v[46:49]
	v_mfma_f32_16x16x32_bf16 v[42:45], v[162:165], v[202:205], v[42:45]
	v_mfma_f32_16x16x32_bf16 v[42:45], v[166:169], v[206:209], v[42:45]
	v_mfma_f32_16x16x32_bf16 v[38:41], v[170:173], v[202:205], v[38:41]
	v_mfma_f32_16x16x32_bf16 v[38:41], v[174:177], v[206:209], v[38:41]
	v_mfma_f32_16x16x32_bf16 v[34:37], v[178:181], v[202:205], v[34:37]
	v_mfma_f32_16x16x32_bf16 v[34:37], v[186:189], v[206:209], v[34:37]
	s_setprio 0
	s_setprio 1
	v_mfma_f32_16x16x32_bf16 v[30:33], v[154:157], v[210:213], v[30:33]
	v_mfma_f32_16x16x32_bf16 v[30:33], v[158:161], v[214:217], v[30:33]
	v_mfma_f32_16x16x32_bf16 v[26:29], v[162:165], v[210:213], v[26:29]
	v_mfma_f32_16x16x32_bf16 v[26:29], v[166:169], v[214:217], v[26:29]
	v_mfma_f32_16x16x32_bf16 v[22:25], v[170:173], v[210:213], v[22:25]
	v_mfma_f32_16x16x32_bf16 v[22:25], v[174:177], v[214:217], v[22:25]
	v_mfma_f32_16x16x32_bf16 v[18:21], v[178:181], v[210:213], v[18:21]
	v_mfma_f32_16x16x32_bf16 v[18:21], v[186:189], v[214:217], v[18:21]
	v_mfma_f32_16x16x32_bf16 v[14:17], v[154:157], v[226:229], v[14:17]
	v_mfma_f32_16x16x32_bf16 v[14:17], v[158:161], v[230:233], v[14:17]
	v_mfma_f32_16x16x32_bf16 v[10:13], v[162:165], v[226:229], v[10:13]
	v_mfma_f32_16x16x32_bf16 v[10:13], v[166:169], v[230:233], v[10:13]
	v_mfma_f32_16x16x32_bf16 v[6:9], v[170:173], v[226:229], v[6:9]
	v_mfma_f32_16x16x32_bf16 v[6:9], v[174:177], v[230:233], v[6:9]
	v_mfma_f32_16x16x32_bf16 v[2:5], v[178:181], v[226:229], v[2:5]
	v_mfma_f32_16x16x32_bf16 v[2:5], v[186:189], v[230:233], v[2:5]
	s_setprio 0
	s_barrier
	s_add_i32 s76, 16, 0x18000
	v_add_u32_e32 v138, s76, v150
	s_add_i32 s77, 16, 0x1c000
	ds_read_b128 v[154:157], v138
	ds_read_b128 v[158:161], v138 offset:1024
	ds_read_b128 v[162:165], v138 offset:2048
	ds_read_b128 v[166:169], v138 offset:3072
	v_add_u32_e32 v138, s77, v150
	ds_read_b128 v[170:173], v138
	ds_read_b128 v[174:177], v138 offset:1024
	ds_read_b128 v[178:181], v138 offset:2048
	ds_read_b128 v[186:189], v138 offset:3072
	s_add_u32 s44, s44, 0x80000
	s_addc_u32 s45, s45, 0
	s_mov_b32 m0, s57
	ds_read_b128 v[190:193], v153 offset:32768
	ds_read_b128 v[194:197], v153 offset:33792
	ds_read_b128 v[202:205], v153 offset:34816
	ds_read_b128 v[206:209], v153 offset:35840
	ds_read_b128 v[210:213], v153 offset:36864
	ds_read_b128 v[214:217], v153 offset:37888
	ds_read_b128 v[226:229], v153 offset:38912
	ds_read_b128 v[230:233], v153 offset:39936
	global_load_lds_dwordx4 v136, s[44:45]
	s_mov_b32 m0, s58
	s_nop 0
	global_load_lds_dwordx4 v132, s[44:45]
	s_waitcnt vmcnt(8)
	s_waitcnt lgkmcnt(0)
	s_barrier
	s_setprio 1
	s_waitcnt lgkmcnt(0)
	v_mfma_f32_16x16x32_bf16 v[126:129], v[154:157], v[190:193], v[126:129]
	v_mfma_f32_16x16x32_bf16 v[126:129], v[158:161], v[194:197], v[126:129]
	v_mfma_f32_16x16x32_bf16 v[122:125], v[162:165], v[190:193], v[122:125]
	v_mfma_f32_16x16x32_bf16 v[122:125], v[166:169], v[194:197], v[122:125]
	v_mfma_f32_16x16x32_bf16 v[118:121], v[170:173], v[190:193], v[118:121]
	v_mfma_f32_16x16x32_bf16 v[118:121], v[174:177], v[194:197], v[118:121]
	v_mfma_f32_16x16x32_bf16 v[114:117], v[178:181], v[190:193], v[114:117]
	v_mfma_f32_16x16x32_bf16 v[114:117], v[186:189], v[194:197], v[114:117]
	v_mfma_f32_16x16x32_bf16 v[110:113], v[154:157], v[202:205], v[110:113]
	v_mfma_f32_16x16x32_bf16 v[110:113], v[158:161], v[206:209], v[110:113]
	v_mfma_f32_16x16x32_bf16 v[106:109], v[162:165], v[202:205], v[106:109]
	v_mfma_f32_16x16x32_bf16 v[106:109], v[166:169], v[206:209], v[106:109]
	v_mfma_f32_16x16x32_bf16 v[102:105], v[170:173], v[202:205], v[102:105]
	v_mfma_f32_16x16x32_bf16 v[102:105], v[174:177], v[206:209], v[102:105]
	v_mfma_f32_16x16x32_bf16 v[98:101], v[178:181], v[202:205], v[98:101]
	v_mfma_f32_16x16x32_bf16 v[98:101], v[186:189], v[206:209], v[98:101]
	s_setprio 0
	s_setprio 1
	v_mfma_f32_16x16x32_bf16 v[94:97], v[154:157], v[210:213], v[94:97]
	v_mfma_f32_16x16x32_bf16 v[94:97], v[158:161], v[214:217], v[94:97]
	v_mfma_f32_16x16x32_bf16 v[90:93], v[162:165], v[210:213], v[90:93]
	v_mfma_f32_16x16x32_bf16 v[90:93], v[166:169], v[214:217], v[90:93]
	v_mfma_f32_16x16x32_bf16 v[86:89], v[170:173], v[210:213], v[86:89]
	v_mfma_f32_16x16x32_bf16 v[86:89], v[174:177], v[214:217], v[86:89]
	v_mfma_f32_16x16x32_bf16 v[82:85], v[178:181], v[210:213], v[82:85]
	v_mfma_f32_16x16x32_bf16 v[82:85], v[186:189], v[214:217], v[82:85]
	v_mfma_f32_16x16x32_bf16 v[78:81], v[154:157], v[226:229], v[78:81]
	v_mfma_f32_16x16x32_bf16 v[78:81], v[158:161], v[230:233], v[78:81]
	v_mfma_f32_16x16x32_bf16 v[74:77], v[162:165], v[226:229], v[74:77]
	v_mfma_f32_16x16x32_bf16 v[74:77], v[166:169], v[230:233], v[74:77]
	v_mfma_f32_16x16x32_bf16 v[70:73], v[170:173], v[226:229], v[70:73]
	v_mfma_f32_16x16x32_bf16 v[70:73], v[174:177], v[230:233], v[70:73]
	v_mfma_f32_16x16x32_bf16 v[66:69], v[178:181], v[226:229], v[66:69]
	v_mfma_f32_16x16x32_bf16 v[66:69], v[186:189], v[230:233], v[66:69]
	s_setprio 0
	s_barrier
	s_add_i32 s44, s76, s53
	s_mov_b32 m0, s44
	s_add_u32 s100, s38, 0x80
	s_addc_u32 s101, s39, 0
	ds_read_b128 v[190:193], v153 offset:49152
	ds_read_b128 v[194:197], v153 offset:50176
	ds_read_b128 v[202:205], v153 offset:51200
	ds_read_b128 v[206:209], v153 offset:52224
	ds_read_b128 v[210:213], v153 offset:53248
	ds_read_b128 v[214:217], v153 offset:54272
	ds_read_b128 v[226:229], v153 offset:55296
	ds_read_b128 v[230:233], v153 offset:56320
	global_load_lds_dwordx4 v134, s[100:101]
	s_add_i32 m0, s44, 0x2000
	s_add_i32 s44, s77, s53
	global_load_lds_dwordx4 v130, s[100:101]
	s_add_u32 s38, s38, 0x80080
	s_addc_u32 s39, s39, 0
	s_mov_b32 m0, s44
	s_nop 0
	global_load_lds_dwordx4 v134, s[38:39]
	s_add_i32 m0, s44, 0x2000
	s_add_u32 s98, s98, 0x80
	s_addc_u32 s99, s99, 0
	global_load_lds_dwordx4 v130, s[38:39]
	s_mov_b32 m0, s62
	s_nop 0
	global_load_lds_dwordx4 v136, s[98:99]
	s_mov_b32 m0, s63
	s_nop 0
	global_load_lds_dwordx4 v132, s[98:99]
	s_waitcnt vmcnt(8)
	s_waitcnt lgkmcnt(0)
	s_barrier
	s_setprio 1
	s_waitcnt lgkmcnt(0)
	v_mfma_f32_16x16x32_bf16 v[62:65], v[154:157], v[190:193], v[62:65]
	v_mfma_f32_16x16x32_bf16 v[62:65], v[158:161], v[194:197], v[62:65]
	v_mfma_f32_16x16x32_bf16 v[58:61], v[162:165], v[190:193], v[58:61]
	v_mfma_f32_16x16x32_bf16 v[58:61], v[166:169], v[194:197], v[58:61]
	v_mfma_f32_16x16x32_bf16 v[54:57], v[170:173], v[190:193], v[54:57]
	v_mfma_f32_16x16x32_bf16 v[54:57], v[174:177], v[194:197], v[54:57]
	v_mfma_f32_16x16x32_bf16 v[50:53], v[178:181], v[190:193], v[50:53]
	v_mfma_f32_16x16x32_bf16 v[50:53], v[186:189], v[194:197], v[50:53]
	v_mfma_f32_16x16x32_bf16 v[46:49], v[154:157], v[202:205], v[46:49]
	v_mfma_f32_16x16x32_bf16 v[46:49], v[158:161], v[206:209], v[46:49]
	v_mfma_f32_16x16x32_bf16 v[42:45], v[162:165], v[202:205], v[42:45]
	v_mfma_f32_16x16x32_bf16 v[42:45], v[166:169], v[206:209], v[42:45]
	v_mfma_f32_16x16x32_bf16 v[38:41], v[170:173], v[202:205], v[38:41]
	v_mfma_f32_16x16x32_bf16 v[38:41], v[174:177], v[206:209], v[38:41]
	v_mfma_f32_16x16x32_bf16 v[34:37], v[178:181], v[202:205], v[34:37]
	v_mfma_f32_16x16x32_bf16 v[34:37], v[186:189], v[206:209], v[34:37]
	s_setprio 0
	s_setprio 1
	v_mfma_f32_16x16x32_bf16 v[30:33], v[154:157], v[210:213], v[30:33]
	v_mfma_f32_16x16x32_bf16 v[30:33], v[158:161], v[214:217], v[30:33]
	v_mfma_f32_16x16x32_bf16 v[26:29], v[162:165], v[210:213], v[26:29]
	v_mfma_f32_16x16x32_bf16 v[26:29], v[166:169], v[214:217], v[26:29]
	v_mfma_f32_16x16x32_bf16 v[22:25], v[170:173], v[210:213], v[22:25]
	v_mfma_f32_16x16x32_bf16 v[22:25], v[174:177], v[214:217], v[22:25]
	v_mfma_f32_16x16x32_bf16 v[18:21], v[178:181], v[210:213], v[18:21]
	v_mfma_f32_16x16x32_bf16 v[18:21], v[186:189], v[214:217], v[18:21]
	v_mfma_f32_16x16x32_bf16 v[14:17], v[154:157], v[226:229], v[14:17]
	v_mfma_f32_16x16x32_bf16 v[14:17], v[158:161], v[230:233], v[14:17]
	v_mfma_f32_16x16x32_bf16 v[10:13], v[162:165], v[226:229], v[10:13]
	v_mfma_f32_16x16x32_bf16 v[10:13], v[166:169], v[230:233], v[10:13]
	v_mfma_f32_16x16x32_bf16 v[6:9], v[170:173], v[226:229], v[6:9]
	v_mfma_f32_16x16x32_bf16 v[6:9], v[174:177], v[230:233], v[6:9]
	v_mfma_f32_16x16x32_bf16 v[2:5], v[178:181], v[226:229], v[2:5]
	v_mfma_f32_16x16x32_bf16 v[2:5], v[186:189], v[230:233], v[2:5]
	s_setprio 0
	s_barrier
	s_add_i32 s74, s74, 2
	s_add_u32 s70, s70, 0x100
	s_addc_u32 s71, s71, 0
	s_add_u32 s36, s36, 0x100
	s_addc_u32 s37, s37, 0
	s_cmp_gt_u32 s74, 29
	s_cbranch_scc0 .LBB0_251
	s_and_b64 vcc, exec, s[20:21]
	s_cbranch_vccz .LBB0_254
	s_barrier

.LBB0_1297:
	ds_read_b128 v[154:157], v150
	ds_read_b128 v[158:161], v150 offset:1024
	ds_read_b128 v[162:165], v150 offset:2048
	ds_read_b128 v[166:169], v150 offset:3072
	ds_read_b128 v[170:173], v151
	ds_read_b128 v[174:177], v151 offset:1024
	ds_read_b128 v[178:181], v151 offset:2048
	ds_read_b128 v[182:185], v151 offset:3072
	s_add_u32 s36, s30, 0xfff80080
	s_addc_u32 s37, s31, -1
	s_cmp_eq_u32 s66, 28
	s_cselect_b32 s39, s23, s37
	s_cselect_b32 s38, s34, s36
	s_cselect_b32 s37, s21, s65
	s_cselect_b32 s36, s35, s64
	s_mov_b64 s[98:99], s[38:39]
	s_add_i32 m0, s29, 0xc000
	ds_read_b128 v[186:189], v152
	ds_read_b128 v[190:193], v152 offset:1024
	ds_read_b128 v[194:197], v152 offset:2048
	ds_read_b128 v[198:201], v152 offset:3072
	ds_read_b128 v[202:205], v152 offset:4096
	ds_read_b128 v[206:209], v152 offset:5120
	ds_read_b128 v[210:213], v152 offset:6144
	ds_read_b128 v[214:217], v152 offset:7168
	global_load_lds_dwordx4 v142, s[30:31]
	s_add_i32 m0, s29, 0xe000
	s_nop 0
	global_load_lds_dwordx4 v140, s[30:31]
	s_waitcnt vmcnt(8)
	s_waitcnt lgkmcnt(0)
	s_barrier
	s_setprio 1
	s_waitcnt lgkmcnt(0)
	v_mfma_f32_16x16x32_bf16 v[126:129], v[154:157], v[186:189], v[126:129]
	v_mfma_f32_16x16x32_bf16 v[126:129], v[158:161], v[190:193], v[126:129]
	v_mfma_f32_16x16x32_bf16 v[122:125], v[162:165], v[186:189], v[122:125]
	v_mfma_f32_16x16x32_bf16 v[122:125], v[166:169], v[190:193], v[122:125]
	v_mfma_f32_16x16x32_bf16 v[118:121], v[170:173], v[186:189], v[118:121]
	v_mfma_f32_16x16x32_bf16 v[118:121], v[174:177], v[190:193], v[118:121]
	v_mfma_f32_16x16x32_bf16 v[114:117], v[178:181], v[186:189], v[114:117]
	v_mfma_f32_16x16x32_bf16 v[114:117], v[182:185], v[190:193], v[114:117]
	v_mfma_f32_16x16x32_bf16 v[110:113], v[154:157], v[194:197], v[110:113]
	v_mfma_f32_16x16x32_bf16 v[110:113], v[158:161], v[198:201], v[110:113]
	v_mfma_f32_16x16x32_bf16 v[106:109], v[162:165], v[194:197], v[106:109]
	v_mfma_f32_16x16x32_bf16 v[106:109], v[166:169], v[198:201], v[106:109]
	v_mfma_f32_16x16x32_bf16 v[102:105], v[170:173], v[194:197], v[102:105]
	v_mfma_f32_16x16x32_bf16 v[102:105], v[174:177], v[198:201], v[102:105]
	v_mfma_f32_16x16x32_bf16 v[98:101], v[178:181], v[194:197], v[98:101]
	v_mfma_f32_16x16x32_bf16 v[98:101], v[182:185], v[198:201], v[98:101]
	s_setprio 0
	s_setprio 1
	v_mfma_f32_16x16x32_bf16 v[94:97], v[154:157], v[202:205], v[94:97]
	v_mfma_f32_16x16x32_bf16 v[94:97], v[158:161], v[206:209], v[94:97]
	v_mfma_f32_16x16x32_bf16 v[90:93], v[162:165], v[202:205], v[90:93]
	v_mfma_f32_16x16x32_bf16 v[90:93], v[166:169], v[206:209], v[90:93]
	v_mfma_f32_16x16x32_bf16 v[86:89], v[170:173], v[202:205], v[86:89]
	v_mfma_f32_16x16x32_bf16 v[86:89], v[174:177], v[206:209], v[86:89]
	v_mfma_f32_16x16x32_bf16 v[82:85], v[178:181], v[202:205], v[82:85]
	v_mfma_f32_16x16x32_bf16 v[82:85], v[182:185], v[206:209], v[82:85]
	v_mfma_f32_16x16x32_bf16 v[78:81], v[154:157], v[210:213], v[78:81]
	v_mfma_f32_16x16x32_bf16 v[78:81], v[158:161], v[214:217], v[78:81]
	v_mfma_f32_16x16x32_bf16 v[74:77], v[162:165], v[210:213], v[74:77]
	v_mfma_f32_16x16x32_bf16 v[74:77], v[166:169], v[214:217], v[74:77]
	v_mfma_f32_16x16x32_bf16 v[70:73], v[170:173], v[210:213], v[70:73]
	v_mfma_f32_16x16x32_bf16 v[70:73], v[174:177], v[214:217], v[70:73]
	v_mfma_f32_16x16x32_bf16 v[66:69], v[178:181], v[210:213], v[66:69]
	v_mfma_f32_16x16x32_bf16 v[66:69], v[182:185], v[214:217], v[66:69]
	s_setprio 0
	s_barrier
	s_add_i32 s67, s60, s48
	s_mov_b32 m0, s67
	ds_read_b128 v[186:189], v152 offset:16384
	ds_read_b128 v[190:193], v152 offset:17408
	ds_read_b128 v[194:197], v152 offset:18432
	ds_read_b128 v[198:201], v152 offset:19456
	ds_read_b128 v[202:205], v152 offset:20480
	ds_read_b128 v[206:209], v152 offset:21504
	ds_read_b128 v[210:213], v152 offset:22528
	ds_read_b128 v[214:217], v152 offset:23552
	global_load_lds_dwordx4 v134, s[36:37]
	s_add_i32 m0, s67, 0x2000
	s_add_u32 s68, s36, 0x80000
	s_addc_u32 s69, s37, 0
	s_add_i32 s67, s61, s48
	global_load_lds_dwordx4 v130, s[36:37]
	s_mov_b32 m0, s67
	s_nop 0
	global_load_lds_dwordx4 v134, s[68:69]
	s_add_i32 m0, s67, 0x2000
	s_nop 0
	global_load_lds_dwordx4 v130, s[68:69]
	s_mov_b32 m0, s29
	s_nop 0
	global_load_lds_dwordx4 v136, s[38:39]
	s_mov_b32 m0, s51
	s_nop 0
	global_load_lds_dwordx4 v132, s[38:39]
	s_waitcnt vmcnt(8)
	s_waitcnt lgkmcnt(0)
	s_barrier
	s_setprio 1
	s_waitcnt lgkmcnt(0)
	v_mfma_f32_16x16x32_bf16 v[62:65], v[154:157], v[186:189], v[62:65]
	v_mfma_f32_16x16x32_bf16 v[62:65], v[158:161], v[190:193], v[62:65]
	v_mfma_f32_16x16x32_bf16 v[58:61], v[162:165], v[186:189], v[58:61]
	v_mfma_f32_16x16x32_bf16 v[58:61], v[166:169], v[190:193], v[58:61]
	v_mfma_f32_16x16x32_bf16 v[54:57], v[170:173], v[186:189], v[54:57]
	v_mfma_f32_16x16x32_bf16 v[54:57], v[174:177], v[190:193], v[54:57]
	v_mfma_f32_16x16x32_bf16 v[50:53], v[178:181], v[186:189], v[50:53]
	v_mfma_f32_16x16x32_bf16 v[50:53], v[182:185], v[190:193], v[50:53]
	v_mfma_f32_16x16x32_bf16 v[46:49], v[154:157], v[194:197], v[46:49]
	v_mfma_f32_16x16x32_bf16 v[46:49], v[158:161], v[198:201], v[46:49]
	v_mfma_f32_16x16x32_bf16 v[42:45], v[162:165], v[194:197], v[42:45]
	v_mfma_f32_16x16x32_bf16 v[42:45], v[166:169], v[198:201], v[42:45]
	v_mfma_f32_16x16x32_bf16 v[38:41], v[170:173], v[194:197], v[38:41]
	v_mfma_f32_16x16x32_bf16 v[38:41], v[174:177], v[198:201], v[38:41]
	v_mfma_f32_16x16x32_bf16 v[34:37], v[178:181], v[194:197], v[34:37]
	v_mfma_f32_16x16x32_bf16 v[34:37], v[182:185], v[198:201], v[34:37]
	s_setprio 0
	s_setprio 1
	v_mfma_f32_16x16x32_bf16 v[30:33], v[154:157], v[202:205], v[30:33]
	v_mfma_f32_16x16x32_bf16 v[30:33], v[158:161], v[206:209], v[30:33]
	v_mfma_f32_16x16x32_bf16 v[26:29], v[162:165], v[202:205], v[26:29]
	v_mfma_f32_16x16x32_bf16 v[26:29], v[166:169], v[206:209], v[26:29]
	v_mfma_f32_16x16x32_bf16 v[22:25], v[170:173], v[202:205], v[22:25]
	v_mfma_f32_16x16x32_bf16 v[22:25], v[174:177], v[206:209], v[22:25]
	v_mfma_f32_16x16x32_bf16 v[18:21], v[178:181], v[202:205], v[18:21]
	v_mfma_f32_16x16x32_bf16 v[18:21], v[182:185], v[206:209], v[18:21]
	v_mfma_f32_16x16x32_bf16 v[14:17], v[154:157], v[210:213], v[14:17]
	v_mfma_f32_16x16x32_bf16 v[14:17], v[158:161], v[214:217], v[14:17]
	v_mfma_f32_16x16x32_bf16 v[10:13], v[162:165], v[210:213], v[10:13]
	v_mfma_f32_16x16x32_bf16 v[10:13], v[166:169], v[214:217], v[10:13]
	v_mfma_f32_16x16x32_bf16 v[6:9], v[170:173], v[210:213], v[6:9]
	v_mfma_f32_16x16x32_bf16 v[6:9], v[174:177], v[214:217], v[6:9]
	v_mfma_f32_16x16x32_bf16 v[2:5], v[178:181], v[210:213], v[2:5]
	v_mfma_f32_16x16x32_bf16 v[2:5], v[182:185], v[214:217], v[2:5]
	s_setprio 0
	s_barrier
	s_add_i32 s67, 16, 0x18000
	v_add_u32_e32 v138, s67, v149
	s_add_i32 s68, 16, 0x1c000
	ds_read_b128 v[154:157], v138
	ds_read_b128 v[158:161], v138 offset:1024
	ds_read_b128 v[162:165], v138 offset:2048
	ds_read_b128 v[166:169], v138 offset:3072
	v_add_u32_e32 v138, s68, v149
	ds_read_b128 v[170:173], v138
	ds_read_b128 v[174:177], v138 offset:1024
	ds_read_b128 v[178:181], v138 offset:2048
	ds_read_b128 v[182:185], v138 offset:3072
	s_add_u32 s38, s38, 0x80000
	s_addc_u32 s39, s39, 0
	s_mov_b32 m0, s52
	ds_read_b128 v[186:189], v152 offset:32768
	ds_read_b128 v[190:193], v152 offset:33792
	ds_read_b128 v[194:197], v152 offset:34816
	ds_read_b128 v[198:201], v152 offset:35840
	ds_read_b128 v[202:205], v152 offset:36864
	ds_read_b128 v[206:209], v152 offset:37888
	ds_read_b128 v[210:213], v152 offset:38912
	ds_read_b128 v[214:217], v152 offset:39936
	global_load_lds_dwordx4 v136, s[38:39]
	s_mov_b32 m0, s53
	s_nop 0
	global_load_lds_dwordx4 v132, s[38:39]
	s_waitcnt vmcnt(8)
	s_waitcnt lgkmcnt(0)
	s_barrier
	s_setprio 1
	s_waitcnt lgkmcnt(0)
	v_mfma_f32_16x16x32_bf16 v[126:129], v[154:157], v[186:189], v[126:129]
	v_mfma_f32_16x16x32_bf16 v[126:129], v[158:161], v[190:193], v[126:129]
	v_mfma_f32_16x16x32_bf16 v[122:125], v[162:165], v[186:189], v[122:125]
	v_mfma_f32_16x16x32_bf16 v[122:125], v[166:169], v[190:193], v[122:125]
	v_mfma_f32_16x16x32_bf16 v[118:121], v[170:173], v[186:189], v[118:121]
	v_mfma_f32_16x16x32_bf16 v[118:121], v[174:177], v[190:193], v[118:121]
	v_mfma_f32_16x16x32_bf16 v[114:117], v[178:181], v[186:189], v[114:117]
	v_mfma_f32_16x16x32_bf16 v[114:117], v[182:185], v[190:193], v[114:117]
	v_mfma_f32_16x16x32_bf16 v[110:113], v[154:157], v[194:197], v[110:113]
	v_mfma_f32_16x16x32_bf16 v[110:113], v[158:161], v[198:201], v[110:113]
	v_mfma_f32_16x16x32_bf16 v[106:109], v[162:165], v[194:197], v[106:109]
	v_mfma_f32_16x16x32_bf16 v[106:109], v[166:169], v[198:201], v[106:109]
	v_mfma_f32_16x16x32_bf16 v[102:105], v[170:173], v[194:197], v[102:105]
	v_mfma_f32_16x16x32_bf16 v[102:105], v[174:177], v[198:201], v[102:105]
	v_mfma_f32_16x16x32_bf16 v[98:101], v[178:181], v[194:197], v[98:101]
	v_mfma_f32_16x16x32_bf16 v[98:101], v[182:185], v[198:201], v[98:101]
	s_setprio 0
	s_setprio 1
	v_mfma_f32_16x16x32_bf16 v[94:97], v[154:157], v[202:205], v[94:97]
	v_mfma_f32_16x16x32_bf16 v[94:97], v[158:161], v[206:209], v[94:97]
	v_mfma_f32_16x16x32_bf16 v[90:93], v[162:165], v[202:205], v[90:93]
	v_mfma_f32_16x16x32_bf16 v[90:93], v[166:169], v[206:209], v[90:93]
	v_mfma_f32_16x16x32_bf16 v[86:89], v[170:173], v[202:205], v[86:89]
	v_mfma_f32_16x16x32_bf16 v[86:89], v[174:177], v[206:209], v[86:89]
	v_mfma_f32_16x16x32_bf16 v[82:85], v[178:181], v[202:205], v[82:85]
	v_mfma_f32_16x16x32_bf16 v[82:85], v[182:185], v[206:209], v[82:85]
	v_mfma_f32_16x16x32_bf16 v[78:81], v[154:157], v[210:213], v[78:81]
	v_mfma_f32_16x16x32_bf16 v[78:81], v[158:161], v[214:217], v[78:81]
	v_mfma_f32_16x16x32_bf16 v[74:77], v[162:165], v[210:213], v[74:77]
	v_mfma_f32_16x16x32_bf16 v[74:77], v[166:169], v[214:217], v[74:77]
	v_mfma_f32_16x16x32_bf16 v[70:73], v[170:173], v[210:213], v[70:73]
	v_mfma_f32_16x16x32_bf16 v[70:73], v[174:177], v[214:217], v[70:73]
	v_mfma_f32_16x16x32_bf16 v[66:69], v[178:181], v[210:213], v[66:69]
	v_mfma_f32_16x16x32_bf16 v[66:69], v[182:185], v[214:217], v[66:69]
	s_setprio 0
	s_barrier
	s_add_i32 s38, s67, s48
	s_mov_b32 m0, s38
	s_add_u32 s100, s36, 0x80
	s_addc_u32 s101, s37, 0
	ds_read_b128 v[186:189], v152 offset:49152
	ds_read_b128 v[190:193], v152 offset:50176
	ds_read_b128 v[194:197], v152 offset:51200
	ds_read_b128 v[198:201], v152 offset:52224
	ds_read_b128 v[202:205], v152 offset:53248
	ds_read_b128 v[206:209], v152 offset:54272
	ds_read_b128 v[210:213], v152 offset:55296
	ds_read_b128 v[214:217], v152 offset:56320
	global_load_lds_dwordx4 v134, s[100:101]
	s_add_i32 m0, s38, 0x2000
	s_add_i32 s38, s68, s48
	global_load_lds_dwordx4 v130, s[100:101]
	s_add_u32 s36, s36, 0x80080
	s_addc_u32 s37, s37, 0
	s_mov_b32 m0, s38
	s_nop 0
	global_load_lds_dwordx4 v134, s[36:37]
	s_add_i32 m0, s38, 0x2000
	s_add_u32 s98, s98, 0x80
	s_addc_u32 s99, s99, 0
	global_load_lds_dwordx4 v130, s[36:37]
	s_mov_b32 m0, s57
	s_nop 0
	global_load_lds_dwordx4 v136, s[98:99]
	s_mov_b32 m0, s58
	s_nop 0
	global_load_lds_dwordx4 v132, s[98:99]
	s_waitcnt vmcnt(8)
	s_waitcnt lgkmcnt(0)
	s_barrier
	s_setprio 1
	s_waitcnt lgkmcnt(0)
	v_mfma_f32_16x16x32_bf16 v[62:65], v[154:157], v[186:189], v[62:65]
	v_mfma_f32_16x16x32_bf16 v[62:65], v[158:161], v[190:193], v[62:65]
	v_mfma_f32_16x16x32_bf16 v[58:61], v[162:165], v[186:189], v[58:61]
	v_mfma_f32_16x16x32_bf16 v[58:61], v[166:169], v[190:193], v[58:61]
	v_mfma_f32_16x16x32_bf16 v[54:57], v[170:173], v[186:189], v[54:57]
	v_mfma_f32_16x16x32_bf16 v[54:57], v[174:177], v[190:193], v[54:57]
	v_mfma_f32_16x16x32_bf16 v[50:53], v[178:181], v[186:189], v[50:53]
	v_mfma_f32_16x16x32_bf16 v[50:53], v[182:185], v[190:193], v[50:53]
	v_mfma_f32_16x16x32_bf16 v[46:49], v[154:157], v[194:197], v[46:49]
	v_mfma_f32_16x16x32_bf16 v[46:49], v[158:161], v[198:201], v[46:49]
	v_mfma_f32_16x16x32_bf16 v[42:45], v[162:165], v[194:197], v[42:45]
	v_mfma_f32_16x16x32_bf16 v[42:45], v[166:169], v[198:201], v[42:45]
	v_mfma_f32_16x16x32_bf16 v[38:41], v[170:173], v[194:197], v[38:41]
	v_mfma_f32_16x16x32_bf16 v[38:41], v[174:177], v[198:201], v[38:41]
	v_mfma_f32_16x16x32_bf16 v[34:37], v[178:181], v[194:197], v[34:37]
	v_mfma_f32_16x16x32_bf16 v[34:37], v[182:185], v[198:201], v[34:37]
	s_setprio 0
	s_setprio 1
	v_mfma_f32_16x16x32_bf16 v[30:33], v[154:157], v[202:205], v[30:33]
	v_mfma_f32_16x16x32_bf16 v[30:33], v[158:161], v[206:209], v[30:33]
	v_mfma_f32_16x16x32_bf16 v[26:29], v[162:165], v[202:205], v[26:29]
	v_mfma_f32_16x16x32_bf16 v[26:29], v[166:169], v[206:209], v[26:29]
	v_mfma_f32_16x16x32_bf16 v[22:25], v[170:173], v[202:205], v[22:25]
	v_mfma_f32_16x16x32_bf16 v[22:25], v[174:177], v[206:209], v[22:25]
	v_mfma_f32_16x16x32_bf16 v[18:21], v[178:181], v[202:205], v[18:21]
	v_mfma_f32_16x16x32_bf16 v[18:21], v[182:185], v[206:209], v[18:21]
	v_mfma_f32_16x16x32_bf16 v[14:17], v[154:157], v[210:213], v[14:17]
	v_mfma_f32_16x16x32_bf16 v[14:17], v[158:161], v[214:217], v[14:17]
	v_mfma_f32_16x16x32_bf16 v[10:13], v[162:165], v[210:213], v[10:13]
	v_mfma_f32_16x16x32_bf16 v[10:13], v[166:169], v[214:217], v[10:13]
	v_mfma_f32_16x16x32_bf16 v[6:9], v[170:173], v[210:213], v[6:9]
	v_mfma_f32_16x16x32_bf16 v[6:9], v[174:177], v[214:217], v[6:9]
	v_mfma_f32_16x16x32_bf16 v[2:5], v[178:181], v[210:213], v[2:5]
	v_mfma_f32_16x16x32_bf16 v[2:5], v[182:185], v[214:217], v[2:5]
	s_setprio 0
	s_barrier
	s_add_i32 s66, s66, 2
	s_add_u32 s64, s64, 0x100
	s_addc_u32 s65, s65, 0
	s_add_u32 s30, s30, 0x100
	s_addc_u32 s31, s31, 0
	s_cmp_gt_u32 s66, 29
	s_cbranch_scc0 .LBB0_1297
	s_and_b64 vcc, exec, s[18:19]
	s_cbranch_vccz .LBB0_1300
	s_barrier
